# final stack + HC score tiles: the four K-operand reads of each tile issued together
# baseline (speedup 1.0000x reference)
.LBB0_183:
	s_waitcnt lgkmcnt(0)
	s_barrier
	ds_read_b128 v[64:67], v130
	ds_read_b128 v[60:63], v130 offset:64
	ds_read_b128 v[56:59], v130 offset:128
	ds_read_b128 v[48:51], v130 offset:192
	ds_read_b128 v[10:13], v131 offset:34816
	ds_read_b128 v[166:169], v131 offset:34880
	ds_read_b128 v[170:173], v131 offset:34944
	ds_read_b128 v[174:177], v131 offset:35008
	s_andn2_b64 vcc, exec, s[58:59]
	s_waitcnt lgkmcnt(3)
	v_mfma_f32_16x16x32_bf16 v[10:13], v[10:13], v[64:67], 0
	s_waitcnt lgkmcnt(2)
	v_mfma_f32_16x16x32_bf16 v[10:13], v[166:169], v[60:63], v[10:13]
	s_waitcnt lgkmcnt(1)
	v_mfma_f32_16x16x32_bf16 v[10:13], v[170:173], v[56:59], v[10:13]
	s_waitcnt lgkmcnt(0)
	v_mfma_f32_16x16x32_bf16 v[52:55], v[174:177], v[48:51], v[10:13]
	s_cbranch_vccz .LBB0_190
	s_andn2_b64 vcc, exec, s[62:63]
	v_mov_b32_e32 v68, 0
	s_cbranch_vccnz .LBB0_191
.LBB0_185:
	s_nop 0
	ds_read_b128 v[10:13], v131 offset:39168
	ds_read_b128 v[178:181], v131 offset:39232
	ds_read_b128 v[182:185], v131 offset:39296
	ds_read_b128 v[186:189], v131 offset:39360
	v_readlane_b32 s34, v254, 41
	v_readlane_b32 s35, v254, 42
	s_andn2_b64 vcc, exec, s[34:35]
	s_waitcnt lgkmcnt(3)
	v_mfma_f32_16x16x32_bf16 v[10:13], v[10:13], v[64:67], 0
	s_waitcnt lgkmcnt(2)
	v_mfma_f32_16x16x32_bf16 v[10:13], v[178:181], v[60:63], v[10:13]
	s_waitcnt lgkmcnt(1)
	v_mfma_f32_16x16x32_bf16 v[10:13], v[182:185], v[56:59], v[10:13]
	s_waitcnt lgkmcnt(0)
	v_mfma_f32_16x16x32_bf16 v[72:75], v[186:189], v[48:51], v[10:13]
	s_cbranch_vccnz .LBB0_187
	s_nop 6
	v_cndmask_b32_e64 v10, v72, 0, s[54:55]
	v_cndmask_b32_e64 v73, 0, v73, s[28:29]
	v_cndmask_b32_e64 v72, v10, v72, s[28:29]
	v_cndmask_b32_e64 v74, v74, 0, s[56:57]
	v_cndmask_b32_e64 v75, v75, 0, s[52:53]

.LBB0_188:
	ds_read_b128 v[10:13], v131 offset:43520
	ds_read_b128 v[190:193], v131 offset:43584
	ds_read_b128 v[194:197], v131 offset:43648
	ds_read_b128 v[198:201], v131 offset:43712
	v_readlane_b32 s34, v254, 35
	v_readlane_b32 s35, v254, 36
	s_andn2_b64 vcc, exec, s[34:35]
	s_waitcnt lgkmcnt(3)
	v_mfma_f32_16x16x32_bf16 v[10:13], v[10:13], v[64:67], 0
	s_waitcnt lgkmcnt(2)
	v_mfma_f32_16x16x32_bf16 v[10:13], v[190:193], v[60:63], v[10:13]
	s_waitcnt lgkmcnt(1)
	v_mfma_f32_16x16x32_bf16 v[10:13], v[194:197], v[56:59], v[10:13]
	s_waitcnt lgkmcnt(0)
	v_mfma_f32_16x16x32_bf16 v[68:71], v[198:201], v[48:51], v[10:13]
	s_cbranch_vccnz .LBB0_193
	s_nop 6
	v_cndmask_b32_e64 v10, v68, 0, s[54:55]
	v_cndmask_b32_e64 v69, 0, v69, s[28:29]
	v_cndmask_b32_e64 v68, v10, v68, s[28:29]
	v_cndmask_b32_e64 v70, v70, 0, s[56:57]
	v_cndmask_b32_e64 v71, v71, 0, s[52:53]
	s_branch .LBB0_193

.LBB0_193:
	v_mov_b32_e32 v12, 0
	s_andn2_b64 vcc, exec, s[64:65]
	v_mov_b32_e32 v13, 0
	v_mov_b32_e32 v14, 0
	v_mov_b32_e32 v15, 0
	s_cbranch_vccnz .LBB0_195
	ds_read_b128 v[10:13], v131 offset:47872
	ds_read_b128 v[210:213], v131 offset:47936
	ds_read_b128 v[214:217], v131 offset:48000
	ds_read_b128 v[218:221], v131 offset:48064
	s_waitcnt lgkmcnt(3)
	v_mfma_f32_16x16x32_bf16 v[10:13], v[10:13], v[64:67], 0
	s_waitcnt lgkmcnt(2)
	v_mfma_f32_16x16x32_bf16 v[10:13], v[210:213], v[60:63], v[10:13]
	s_waitcnt lgkmcnt(1)
	v_mfma_f32_16x16x32_bf16 v[10:13], v[214:217], v[56:59], v[10:13]
	s_waitcnt lgkmcnt(0)
	v_mfma_f32_16x16x32_bf16 v[12:15], v[218:221], v[48:51], v[10:13]
	s_nop 7
	v_cndmask_b32_e64 v10, v12, 0, s[54:55]
	v_cndmask_b32_e64 v12, v10, v12, s[28:29]
	v_cndmask_b32_e64 v13, 0, v13, s[28:29]
	v_cndmask_b32_e64 v14, v14, 0, s[56:57]
	v_cndmask_b32_e64 v15, v15, 0, s[52:53]
